# LayerNorm phases: wave sums by DPP adds + permlane16/32 swaps instead of six ds_bpermute round trips per reduction
# speedup vs baseline: 1.0082x; 1.0082x over previous
.LBB0_937:
	s_mov_b32 s4, 0x3e0f83e1
	v_mul_hi_i32 v0, v41, s4
	v_lshrrev_b32_e32 v1, 31, v0
	v_ashrrev_i32_e32 v0, 11, v0
	v_add_u32_e32 v42, v0, v1
	s_movk_i32 s4, 0xdf00
	v_mad_i32_i24 v1, v42, s4, v41
	s_movk_i32 s4, 0x100
	v_cmp_gt_i32_e64 s[12:13], s4, v1
	s_movk_i32 s4, 0xff
	v_cmp_lt_i32_e32 vcc, s4, v1
	s_and_saveexec_b64 s[4:5], vcc
	s_xor_b64 s[4:5], exec, s[4:5]
	v_mul_i32_i24_e32 v0, 0xffffdf00, v42
	v_lshl_add_u32 v0, v42, 13, v0
	v_add3_u32 v0, v41, v0, s2
	s_or_saveexec_b64 s[4:5], s[4:5]
	v_mov_b64_e32 v[2:3], s[88:89]
	s_xor_b64 exec, exec, s[4:5]
	v_lshl_add_u32 v0, v42, 8, v1
	v_mov_b64_e32 v[2:3], s[70:71]
	s_or_b64 exec, exec, s[4:5]
	v_ashrrev_i32_e32 v1, 31, v0
	v_lshlrev_b64 v[0:1], 12, v[0:1]
	v_lshl_add_u64 v[0:1], v[2:3], 0, v[0:1]
	v_lshl_add_u64 v[0:1], v[0:1], 0, v[24:25]
	global_load_dwordx4 v[12:15], v[0:1], off
	global_load_dwordx4 v[8:11], v[0:1], off offset:1024
	global_load_dwordx4 v[4:7], v[0:1], off offset:2048
	s_nop 0
	global_load_dwordx4 v[0:3], v[0:1], off offset:3072
	s_waitcnt vmcnt(3)
	v_mov_b32_e32 v32, v13
	v_mov_b32_e32 v33, v14
	v_mov_b32_e32 v44, v12
	v_mov_b32_e32 v45, v15
	s_waitcnt vmcnt(2)
	v_mov_b32_e32 v46, v9
	v_mov_b32_e32 v47, v10
	v_mov_b32_e32 v48, v8
	v_mov_b32_e32 v49, v11
	v_pk_add_f32 v[32:33], v[32:33], v[44:45]
	v_pk_add_f32 v[44:45], v[46:47], v[48:49]
	v_add_f32_e32 v43, v32, v33
	v_pk_add_f32 v[32:33], v[44:45], v[44:45] op_sel:[0,1] op_sel_hi:[1,0]
	s_waitcnt vmcnt(1)
	v_add_f32_e32 v50, v4, v5
	v_add_f32_e32 v52, v6, v7
	s_waitcnt vmcnt(0)
	v_mov_b32_e32 v55, v0
	v_mov_b32_e32 v51, v2
	v_mov_b32_e32 v53, v3
	v_add_f32_e32 v54, 0, v43
	v_mov_b32_e32 v33, v1
	v_pk_add_f32 v[46:47], v[50:51], v[52:53]
	v_pk_add_f32 v[32:33], v[54:55], v[32:33]
	s_nop 0
	v_pk_add_f32 v[32:33], v[32:33], v[46:47]
	s_nop 0
	v_add_f32_e32 v32, v32, v33
	s_nop 1
	v_add_f32_dpp v32, v32, v32 quad_perm:[1,0,3,2] row_mask:0xf bank_mask:0xf
	s_nop 1
	v_add_f32_dpp v32, v32, v32 quad_perm:[2,3,0,1] row_mask:0xf bank_mask:0xf
	s_nop 1
	v_add_f32_dpp v32, v32, v32 row_half_mirror row_mask:0xf bank_mask:0xf
	s_nop 1
	v_add_f32_dpp v32, v32, v32 row_mirror row_mask:0xf bank_mask:0xf
	v_mov_b32_e32 v33, v32
	s_nop 1
	v_permlane16_swap_b32 v32, v33
	v_add_f32_e32 v32, v32, v33
	v_mov_b32_e32 v33, v32
	s_nop 1
	v_permlane32_swap_b32 v32, v33
	v_add_f32_e32 v43, v32, v33
	v_fmamk_f32 v33, v43, 0xba800000, v15
	v_fmamk_f32 v32, v43, 0xba800000, v14
	v_fmamk_f32 v13, v43, 0xba800000, v13
	v_fmac_f32_e32 v12, 0xba800000, v43
	v_fmamk_f32 v11, v43, 0xba800000, v11
	v_fmamk_f32 v10, v43, 0xba800000, v10
	v_fmamk_f32 v9, v43, 0xba800000, v9
	v_fmac_f32_e32 v8, 0xba800000, v43
	v_pk_mul_f32 v[14:15], v[32:33], v[32:33]
	v_pk_mul_f32 v[44:45], v[12:13], v[12:13]
	v_pk_mul_f32 v[46:47], v[10:11], v[10:11]
	v_pk_mul_f32 v[48:49], v[8:9], v[8:9]
	v_fmamk_f32 v6, v43, 0xba800000, v6
	v_fmac_f32_e32 v4, 0xba800000, v43
	v_pk_mov_b32 v[54:55], v[44:45], v[14:15] op_sel:[1,0]
	v_mov_b32_e32 v45, v15
	v_pk_mov_b32 v[14:15], v[48:49], v[46:47] op_sel:[1,0]
	v_mov_b32_e32 v49, v47
	v_fmamk_f32 v7, v43, 0xba800000, v7
	v_fmamk_f32 v5, v43, 0xba800000, v5
	v_mul_f32_e32 v50, v4, v4
	v_mul_f32_e32 v52, v6, v6
	v_pk_add_f32 v[44:45], v[54:55], v[44:45]
	v_pk_add_f32 v[14:15], v[14:15], v[48:49]
	v_fmamk_f32 v3, v43, 0xba800000, v3
	v_fmamk_f32 v2, v43, 0xba800000, v2
	v_fmamk_f32 v1, v43, 0xba800000, v1
	v_fmac_f32_e32 v0, 0xba800000, v43
	v_pk_fma_f32 v[46:47], v[4:5], v[4:5], v[50:51] op_sel_hi:[1,1,0]
	v_pk_fma_f32 v[50:51], v[6:7], v[6:7], v[52:53] op_sel_hi:[1,1,0]
	v_pk_add_f32 v[44:45], v[44:45], v[44:45] op_sel_hi:[0,1]
	v_pk_add_f32 v[14:15], v[14:15], v[14:15] op_sel_hi:[0,1]
	v_mul_f32_e32 v46, v0, v0
	v_mul_f32_e32 v50, v1, v1
	v_mul_f32_e32 v44, v2, v2
	v_mul_f32_e32 v14, v3, v3
	v_pk_add_f32 v[46:47], v[46:47], v[50:51]
	v_pk_add_f32 v[14:15], v[44:45], v[14:15]
	s_nop 0
	v_pk_add_f32 v[14:15], v[46:47], v[14:15]
	s_nop 0
	v_add_f32_e32 v14, v14, v15
	s_nop 1
	v_add_f32_dpp v14, v14, v14 quad_perm:[1,0,3,2] row_mask:0xf bank_mask:0xf
	s_nop 1
	v_add_f32_dpp v14, v14, v14 quad_perm:[2,3,0,1] row_mask:0xf bank_mask:0xf
	s_nop 1
	v_add_f32_dpp v14, v14, v14 row_half_mirror row_mask:0xf bank_mask:0xf
	s_nop 1
	v_add_f32_dpp v14, v14, v14 row_mirror row_mask:0xf bank_mask:0xf
	v_mov_b32_e32 v15, v14
	s_nop 1
	v_permlane16_swap_b32 v14, v15
	v_add_f32_e32 v14, v14, v15
	v_mov_b32_e32 v15, v14
	s_nop 1
	v_permlane32_swap_b32 v14, v15
	v_add_f32_e32 v14, v14, v15
	v_fmamk_f32 v14, v14, 0x3a800000, v40
	v_mul_f32_e32 v15, 0x4b800000, v14
	v_cmp_gt_f32_e32 vcc, s6, v14
	s_nop 1
	v_cndmask_b32_e32 v14, v14, v15, vcc
	v_rsq_f32_e32 v14, v14
	s_nop 0
	v_mul_f32_e32 v15, 0x45800000, v14
	v_cndmask_b32_e32 v14, v14, v15, vcc
	s_and_saveexec_b64 s[4:5], s[10:11]
	s_cbranch_execz .LBB0_936
	v_lshl_add_u64 v[46:47], s[90:91], 0, v[20:21]
	v_add_co_u32_e32 v46, vcc, 0x1fe00000, v46
	v_mul_f32_e32 v44, 0x3a800000, v43
	s_nop 0
	v_addc_co_u32_e32 v47, vcc, 0, v47, vcc
	v_mov_b32_e32 v45, v14
	global_store_dwordx2 v[46:47], v[44:45], off
	s_branch .LBB0_936

.LBB0_1257:
	s_mov_b32 s4, 0x3e0f83e1
	v_mul_hi_i32 v0, v53, s4
	v_lshrrev_b32_e32 v1, 31, v0
	v_ashrrev_i32_e32 v0, 11, v0
	v_add_u32_e32 v54, v0, v1
	v_mad_i32_i24 v1, v54, s2, v53
	s_movk_i32 s4, 0x100
	v_cmp_gt_i32_e64 s[12:13], s4, v1
	v_cmp_lt_i32_e32 vcc, s6, v1
	s_and_saveexec_b64 s[4:5], vcc
	s_xor_b64 s[4:5], exec, s[4:5]
	v_mul_i32_i24_e32 v0, 0xffffdf00, v54
	v_lshl_add_u32 v0, v54, 13, v0
	v_add3_u32 v0, v53, v0, s7
	s_or_saveexec_b64 s[4:5], s[4:5]
	v_readlane_b32 s16, v254, 28
	v_readlane_b32 s20, v254, 32
	v_readlane_b32 s21, v254, 33
	v_readlane_b32 s17, v254, 29
	v_readlane_b32 s18, v254, 30
	v_mov_b64_e32 v[2:3], s[20:21]
	v_readlane_b32 s19, v254, 31
	v_readlane_b32 s22, v254, 34
	v_readlane_b32 s23, v254, 35
	s_xor_b64 exec, exec, s[4:5]
	v_lshl_add_u32 v0, v54, 8, v1
	v_mov_b64_e32 v[2:3], s[70:71]
	s_or_b64 exec, exec, s[4:5]
	v_ashrrev_i32_e32 v1, 31, v0
	v_lshlrev_b64 v[0:1], 12, v[0:1]
	v_lshl_add_u64 v[0:1], v[2:3], 0, v[0:1]
	v_lshl_add_u64 v[0:1], v[0:1], 0, v[36:37]
	global_load_dwordx4 v[12:15], v[0:1], off
	global_load_dwordx4 v[8:11], v[0:1], off offset:1024
	global_load_dwordx4 v[4:7], v[0:1], off offset:2048
	s_nop 0
	global_load_dwordx4 v[0:3], v[0:1], off offset:3072
	s_waitcnt vmcnt(3)
	v_mov_b32_e32 v44, v13
	v_mov_b32_e32 v45, v14
	v_mov_b32_e32 v56, v12
	v_mov_b32_e32 v57, v15
	s_waitcnt vmcnt(2)
	v_mov_b32_e32 v58, v9
	v_mov_b32_e32 v59, v10
	v_mov_b32_e32 v60, v8
	v_mov_b32_e32 v61, v11
	v_pk_add_f32 v[44:45], v[44:45], v[56:57]
	v_pk_add_f32 v[56:57], v[58:59], v[60:61]
	v_add_f32_e32 v55, v44, v45
	v_pk_add_f32 v[44:45], v[56:57], v[56:57] op_sel:[0,1] op_sel_hi:[1,0]
	s_waitcnt vmcnt(1)
	v_add_f32_e32 v62, v4, v5
	v_add_f32_e32 v64, v6, v7
	s_waitcnt vmcnt(0)
	v_mov_b32_e32 v67, v0
	v_mov_b32_e32 v63, v2
	v_mov_b32_e32 v65, v3
	v_add_f32_e32 v66, 0, v55
	v_mov_b32_e32 v45, v1
	v_pk_add_f32 v[58:59], v[62:63], v[64:65]
	v_pk_add_f32 v[44:45], v[66:67], v[44:45]
	s_nop 0
	v_pk_add_f32 v[44:45], v[44:45], v[58:59]
	s_nop 0
	v_add_f32_e32 v44, v44, v45
	s_nop 1
	v_add_f32_dpp v44, v44, v44 quad_perm:[1,0,3,2] row_mask:0xf bank_mask:0xf
	s_nop 1
	v_add_f32_dpp v44, v44, v44 quad_perm:[2,3,0,1] row_mask:0xf bank_mask:0xf
	s_nop 1
	v_add_f32_dpp v44, v44, v44 row_half_mirror row_mask:0xf bank_mask:0xf
	s_nop 1
	v_add_f32_dpp v44, v44, v44 row_mirror row_mask:0xf bank_mask:0xf
	v_mov_b32_e32 v45, v44
	s_nop 1
	v_permlane16_swap_b32 v44, v45
	v_add_f32_e32 v44, v44, v45
	v_mov_b32_e32 v45, v44
	s_nop 1
	v_permlane32_swap_b32 v44, v45
	v_add_f32_e32 v55, v44, v45
	v_fmamk_f32 v45, v55, 0xba800000, v15
	v_fmamk_f32 v44, v55, 0xba800000, v14
	v_fmamk_f32 v13, v55, 0xba800000, v13
	v_fmac_f32_e32 v12, 0xba800000, v55
	v_fmamk_f32 v11, v55, 0xba800000, v11
	v_fmamk_f32 v10, v55, 0xba800000, v10
	v_fmamk_f32 v9, v55, 0xba800000, v9
	v_fmac_f32_e32 v8, 0xba800000, v55
	v_pk_mul_f32 v[14:15], v[44:45], v[44:45]
	v_pk_mul_f32 v[56:57], v[12:13], v[12:13]
	v_pk_mul_f32 v[58:59], v[10:11], v[10:11]
	v_pk_mul_f32 v[60:61], v[8:9], v[8:9]
	v_fmamk_f32 v6, v55, 0xba800000, v6
	v_fmac_f32_e32 v4, 0xba800000, v55
	v_pk_mov_b32 v[66:67], v[56:57], v[14:15] op_sel:[1,0]
	v_mov_b32_e32 v57, v15
	v_pk_mov_b32 v[14:15], v[60:61], v[58:59] op_sel:[1,0]
	v_mov_b32_e32 v61, v59
	v_fmamk_f32 v7, v55, 0xba800000, v7
	v_fmamk_f32 v5, v55, 0xba800000, v5
	v_mul_f32_e32 v62, v4, v4
	v_mul_f32_e32 v64, v6, v6
	v_pk_add_f32 v[56:57], v[66:67], v[56:57]
	v_pk_add_f32 v[14:15], v[14:15], v[60:61]
	v_fmamk_f32 v3, v55, 0xba800000, v3
	v_fmamk_f32 v2, v55, 0xba800000, v2
	v_fmamk_f32 v1, v55, 0xba800000, v1
	v_fmac_f32_e32 v0, 0xba800000, v55
	v_pk_fma_f32 v[58:59], v[4:5], v[4:5], v[62:63] op_sel_hi:[1,1,0]
	v_pk_fma_f32 v[62:63], v[6:7], v[6:7], v[64:65] op_sel_hi:[1,1,0]
	v_pk_add_f32 v[56:57], v[56:57], v[56:57] op_sel_hi:[0,1]
	v_pk_add_f32 v[14:15], v[14:15], v[14:15] op_sel_hi:[0,1]
	v_mul_f32_e32 v58, v0, v0
	v_mul_f32_e32 v62, v1, v1
	v_mul_f32_e32 v56, v2, v2
	v_mul_f32_e32 v14, v3, v3
	v_pk_add_f32 v[58:59], v[58:59], v[62:63]
	v_pk_add_f32 v[14:15], v[56:57], v[14:15]
	s_nop 0
	v_pk_add_f32 v[14:15], v[58:59], v[14:15]
	s_nop 0
	v_add_f32_e32 v14, v14, v15
	s_nop 1
	v_add_f32_dpp v14, v14, v14 quad_perm:[1,0,3,2] row_mask:0xf bank_mask:0xf
	s_nop 1
	v_add_f32_dpp v14, v14, v14 quad_perm:[2,3,0,1] row_mask:0xf bank_mask:0xf
	s_nop 1
	v_add_f32_dpp v14, v14, v14 row_half_mirror row_mask:0xf bank_mask:0xf
	s_nop 1
	v_add_f32_dpp v14, v14, v14 row_mirror row_mask:0xf bank_mask:0xf
	v_mov_b32_e32 v15, v14
	s_nop 1
	v_permlane16_swap_b32 v14, v15
	v_add_f32_e32 v14, v14, v15
	v_mov_b32_e32 v15, v14
	s_nop 1
	v_permlane32_swap_b32 v14, v15
	v_add_f32_e32 v14, v14, v15
	v_fmamk_f32 v14, v14, 0x3a800000, v52
	v_mul_f32_e32 v15, 0x4b800000, v14
	v_cmp_gt_f32_e32 vcc, s26, v14
	s_nop 1
	v_cndmask_b32_e32 v14, v14, v15, vcc
	v_rsq_f32_e32 v14, v14
	s_nop 0
	v_mul_f32_e32 v15, 0x45800000, v14
	v_cndmask_b32_e32 v14, v14, v15, vcc
	s_and_saveexec_b64 s[4:5], s[10:11]
	s_cbranch_execz .LBB0_1256
	v_readlane_b32 s16, v254, 28
	v_readlane_b32 s22, v254, 34
	v_readlane_b32 s23, v254, 35
	v_mul_f32_e32 v56, 0x3a800000, v55
	v_mov_b32_e32 v57, v14
	v_lshl_add_u64 v[58:59], s[22:23], 0, v[32:33]
	v_add_co_u32_e32 v58, vcc, 0x1fe00000, v58
	v_readlane_b32 s17, v254, 29
	s_nop 0
	v_addc_co_u32_e32 v59, vcc, 0, v59, vcc
	v_readlane_b32 s18, v254, 30
	v_readlane_b32 s19, v254, 31
	v_readlane_b32 s20, v254, 32
	v_readlane_b32 s21, v254, 33
	global_store_dwordx2 v[58:59], v[56:57], off
	s_branch .LBB0_1256

.LBB0_1847:
	v_mul_hi_i32 v0, v53, s6
	v_lshrrev_b32_e32 v1, 31, v0
	v_ashrrev_i32_e32 v0, 11, v0
	v_add_u32_e32 v54, v0, v1
	v_mad_i32_i24 v1, v54, s7, v53
	v_cmp_gt_i32_e64 s[10:11], s2, v1
	v_cmp_lt_i32_e32 vcc, s28, v1
	s_and_saveexec_b64 s[4:5], vcc
	s_xor_b64 s[4:5], exec, s[4:5]
	v_mul_i32_i24_e32 v0, 0xffffdf00, v54
	v_lshl_add_u32 v0, v54, 13, v0
	v_add3_u32 v0, v53, v0, s29
	s_or_saveexec_b64 s[4:5], s[4:5]
	v_readlane_b32 s16, v254, 28
	v_readlane_b32 s20, v254, 32
	v_readlane_b32 s21, v254, 33
	v_readlane_b32 s17, v254, 29
	v_readlane_b32 s18, v254, 30
	v_mov_b64_e32 v[2:3], s[20:21]
	v_readlane_b32 s19, v254, 31
	v_readlane_b32 s22, v254, 34
	v_readlane_b32 s23, v254, 35
	s_xor_b64 exec, exec, s[4:5]
	v_lshl_add_u32 v0, v54, 8, v1
	v_mov_b64_e32 v[2:3], s[70:71]
	s_or_b64 exec, exec, s[4:5]
	v_ashrrev_i32_e32 v1, 31, v0
	v_lshlrev_b64 v[0:1], 12, v[0:1]
	v_lshl_add_u64 v[0:1], v[2:3], 0, v[0:1]
	v_lshl_add_u64 v[0:1], v[0:1], 0, v[36:37]
	global_load_dwordx4 v[12:15], v[0:1], off
	global_load_dwordx4 v[8:11], v[0:1], off offset:1024
	global_load_dwordx4 v[4:7], v[0:1], off offset:2048
	s_nop 0
	global_load_dwordx4 v[0:3], v[0:1], off offset:3072
	s_waitcnt vmcnt(3)
	v_mov_b32_e32 v44, v13
	v_mov_b32_e32 v45, v14
	v_mov_b32_e32 v56, v12
	v_mov_b32_e32 v57, v15
	s_waitcnt vmcnt(2)
	v_mov_b32_e32 v58, v9
	v_mov_b32_e32 v59, v10
	v_mov_b32_e32 v60, v8
	v_mov_b32_e32 v61, v11
	v_pk_add_f32 v[44:45], v[44:45], v[56:57]
	v_pk_add_f32 v[56:57], v[58:59], v[60:61]
	v_add_f32_e32 v55, v44, v45
	v_pk_add_f32 v[44:45], v[56:57], v[56:57] op_sel:[0,1] op_sel_hi:[1,0]
	s_waitcnt vmcnt(1)
	v_add_f32_e32 v62, v4, v5
	v_add_f32_e32 v64, v6, v7
	s_waitcnt vmcnt(0)
	v_mov_b32_e32 v67, v0
	v_mov_b32_e32 v63, v2
	v_mov_b32_e32 v65, v3
	v_add_f32_e32 v66, 0, v55
	v_mov_b32_e32 v45, v1
	v_pk_add_f32 v[58:59], v[62:63], v[64:65]
	v_pk_add_f32 v[44:45], v[66:67], v[44:45]
	s_nop 0
	v_pk_add_f32 v[44:45], v[44:45], v[58:59]
	s_nop 0
	v_add_f32_e32 v44, v44, v45
	s_nop 1
	v_add_f32_dpp v44, v44, v44 quad_perm:[1,0,3,2] row_mask:0xf bank_mask:0xf
	s_nop 1
	v_add_f32_dpp v44, v44, v44 quad_perm:[2,3,0,1] row_mask:0xf bank_mask:0xf
	s_nop 1
	v_add_f32_dpp v44, v44, v44 row_half_mirror row_mask:0xf bank_mask:0xf
	s_nop 1
	v_add_f32_dpp v44, v44, v44 row_mirror row_mask:0xf bank_mask:0xf
	v_mov_b32_e32 v45, v44
	s_nop 1
	v_permlane16_swap_b32 v44, v45
	v_add_f32_e32 v44, v44, v45
	v_mov_b32_e32 v45, v44
	s_nop 1
	v_permlane32_swap_b32 v44, v45
	v_add_f32_e32 v55, v44, v45
	v_fmamk_f32 v45, v55, 0xba800000, v15
	v_fmamk_f32 v44, v55, 0xba800000, v14
	v_fmamk_f32 v13, v55, 0xba800000, v13
	v_fmac_f32_e32 v12, 0xba800000, v55
	v_fmamk_f32 v11, v55, 0xba800000, v11
	v_fmamk_f32 v10, v55, 0xba800000, v10
	v_fmamk_f32 v9, v55, 0xba800000, v9
	v_fmac_f32_e32 v8, 0xba800000, v55
	v_pk_mul_f32 v[14:15], v[44:45], v[44:45]
	v_pk_mul_f32 v[56:57], v[12:13], v[12:13]
	v_pk_mul_f32 v[58:59], v[10:11], v[10:11]
	v_pk_mul_f32 v[60:61], v[8:9], v[8:9]
	v_fmamk_f32 v6, v55, 0xba800000, v6
	v_fmac_f32_e32 v4, 0xba800000, v55
	v_pk_mov_b32 v[66:67], v[56:57], v[14:15] op_sel:[1,0]
	v_mov_b32_e32 v57, v15
	v_pk_mov_b32 v[14:15], v[60:61], v[58:59] op_sel:[1,0]
	v_mov_b32_e32 v61, v59
	v_fmamk_f32 v7, v55, 0xba800000, v7
	v_fmamk_f32 v5, v55, 0xba800000, v5
	v_mul_f32_e32 v62, v4, v4
	v_mul_f32_e32 v64, v6, v6
	v_pk_add_f32 v[56:57], v[66:67], v[56:57]
	v_pk_add_f32 v[14:15], v[14:15], v[60:61]
	v_fmamk_f32 v3, v55, 0xba800000, v3
	v_fmamk_f32 v2, v55, 0xba800000, v2
	v_fmamk_f32 v1, v55, 0xba800000, v1
	v_fmac_f32_e32 v0, 0xba800000, v55
	v_pk_fma_f32 v[58:59], v[4:5], v[4:5], v[62:63] op_sel_hi:[1,1,0]
	v_pk_fma_f32 v[62:63], v[6:7], v[6:7], v[64:65] op_sel_hi:[1,1,0]
	v_pk_add_f32 v[56:57], v[56:57], v[56:57] op_sel_hi:[0,1]
	v_pk_add_f32 v[14:15], v[14:15], v[14:15] op_sel_hi:[0,1]
	v_mul_f32_e32 v58, v0, v0
	v_mul_f32_e32 v62, v1, v1
	v_mul_f32_e32 v56, v2, v2
	v_mul_f32_e32 v14, v3, v3
	v_pk_add_f32 v[58:59], v[58:59], v[62:63]
	v_pk_add_f32 v[14:15], v[56:57], v[14:15]
	s_nop 0
	v_pk_add_f32 v[14:15], v[58:59], v[14:15]
	s_nop 0
	v_add_f32_e32 v14, v14, v15
	s_nop 1
	v_add_f32_dpp v14, v14, v14 quad_perm:[1,0,3,2] row_mask:0xf bank_mask:0xf
	s_nop 1
	v_add_f32_dpp v14, v14, v14 quad_perm:[2,3,0,1] row_mask:0xf bank_mask:0xf
	s_nop 1
	v_add_f32_dpp v14, v14, v14 row_half_mirror row_mask:0xf bank_mask:0xf
	s_nop 1
	v_add_f32_dpp v14, v14, v14 row_mirror row_mask:0xf bank_mask:0xf
	v_mov_b32_e32 v15, v14
	s_nop 1
	v_permlane16_swap_b32 v14, v15
	v_add_f32_e32 v14, v14, v15
	v_mov_b32_e32 v15, v14
	s_nop 1
	v_permlane32_swap_b32 v14, v15
	v_add_f32_e32 v14, v14, v15
	v_fmamk_f32 v14, v14, 0x3a800000, v52
	v_mul_f32_e32 v15, 0x4b800000, v14
	v_cmp_gt_f32_e32 vcc, s30, v14
	s_nop 1
	v_cndmask_b32_e32 v14, v14, v15, vcc
	v_rsq_f32_e32 v14, v14
	s_nop 0
	v_mul_f32_e32 v15, 0x45800000, v14
	v_cndmask_b32_e32 v14, v14, v15, vcc
	s_and_saveexec_b64 s[4:5], s[8:9]
	s_cbranch_execz .LBB0_1846
	v_readlane_b32 s16, v254, 28
	v_readlane_b32 s22, v254, 34
	v_readlane_b32 s23, v254, 35
	v_mul_f32_e32 v56, 0x3a800000, v55
	v_mov_b32_e32 v57, v14
	v_lshl_add_u64 v[58:59], s[22:23], 0, v[32:33]
	v_add_co_u32_e32 v58, vcc, 0x1fe00000, v58
	v_readlane_b32 s17, v254, 29
	s_nop 0
	v_addc_co_u32_e32 v59, vcc, 0, v59, vcc
	v_readlane_b32 s18, v254, 30
	v_readlane_b32 s19, v254, 31
	v_readlane_b32 s20, v254, 32
	v_readlane_b32 s21, v254, 33
	global_store_dwordx2 v[58:59], v[56:57], off
	s_branch .LBB0_1846

.LBB0_2075:
	v_mul_hi_i32 v0, v53, s6
	v_lshrrev_b32_e32 v1, 31, v0
	v_ashrrev_i32_e32 v0, 11, v0
	v_add_u32_e32 v54, v0, v1
	v_mad_i32_i24 v1, v54, s7, v53
	v_cmp_gt_i32_e64 s[12:13], s2, v1
	v_cmp_lt_i32_e32 vcc, s8, v1
	s_and_saveexec_b64 s[4:5], vcc
	s_xor_b64 s[4:5], exec, s[4:5]
	v_mul_i32_i24_e32 v0, 0xffffdf00, v54
	v_lshl_add_u32 v0, v54, 13, v0
	v_add3_u32 v0, v53, v0, s9
	s_or_saveexec_b64 s[4:5], s[4:5]
	v_readlane_b32 s36, v254, 28
	v_readlane_b32 s40, v254, 32
	v_readlane_b32 s41, v254, 33
	v_readlane_b32 s37, v254, 29
	v_readlane_b32 s38, v254, 30
	v_mov_b64_e32 v[2:3], s[40:41]
	v_readlane_b32 s39, v254, 31
	v_readlane_b32 s42, v254, 34
	v_readlane_b32 s43, v254, 35
	s_xor_b64 exec, exec, s[4:5]
	v_lshl_add_u32 v0, v54, 8, v1
	v_mov_b64_e32 v[2:3], s[70:71]
	s_or_b64 exec, exec, s[4:5]
	v_ashrrev_i32_e32 v1, 31, v0
	v_lshlrev_b64 v[0:1], 12, v[0:1]
	v_lshl_add_u64 v[0:1], v[2:3], 0, v[0:1]
	v_lshl_add_u64 v[0:1], v[0:1], 0, v[36:37]
	global_load_dwordx4 v[12:15], v[0:1], off
	global_load_dwordx4 v[8:11], v[0:1], off offset:1024
	global_load_dwordx4 v[4:7], v[0:1], off offset:2048
	s_nop 0
	global_load_dwordx4 v[0:3], v[0:1], off offset:3072
	s_waitcnt vmcnt(3)
	v_mov_b32_e32 v44, v13
	v_mov_b32_e32 v45, v14
	v_mov_b32_e32 v56, v12
	v_mov_b32_e32 v57, v15
	s_waitcnt vmcnt(2)
	v_mov_b32_e32 v58, v9
	v_mov_b32_e32 v59, v10
	v_mov_b32_e32 v60, v8
	v_mov_b32_e32 v61, v11
	v_pk_add_f32 v[44:45], v[44:45], v[56:57]
	v_pk_add_f32 v[56:57], v[58:59], v[60:61]
	v_add_f32_e32 v55, v44, v45
	v_pk_add_f32 v[44:45], v[56:57], v[56:57] op_sel:[0,1] op_sel_hi:[1,0]
	s_waitcnt vmcnt(1)
	v_add_f32_e32 v62, v4, v5
	v_add_f32_e32 v64, v6, v7
	s_waitcnt vmcnt(0)
	v_mov_b32_e32 v67, v0
	v_mov_b32_e32 v63, v2
	v_mov_b32_e32 v65, v3
	v_add_f32_e32 v66, 0, v55
	v_mov_b32_e32 v45, v1
	v_pk_add_f32 v[58:59], v[62:63], v[64:65]
	v_pk_add_f32 v[44:45], v[66:67], v[44:45]
	s_nop 0
	v_pk_add_f32 v[44:45], v[44:45], v[58:59]
	s_nop 0
	v_add_f32_e32 v44, v44, v45
	s_nop 1
	v_add_f32_dpp v44, v44, v44 quad_perm:[1,0,3,2] row_mask:0xf bank_mask:0xf
	s_nop 1
	v_add_f32_dpp v44, v44, v44 quad_perm:[2,3,0,1] row_mask:0xf bank_mask:0xf
	s_nop 1
	v_add_f32_dpp v44, v44, v44 row_half_mirror row_mask:0xf bank_mask:0xf
	s_nop 1
	v_add_f32_dpp v44, v44, v44 row_mirror row_mask:0xf bank_mask:0xf
	v_mov_b32_e32 v45, v44
	s_nop 1
	v_permlane16_swap_b32 v44, v45
	v_add_f32_e32 v44, v44, v45
	v_mov_b32_e32 v45, v44
	s_nop 1
	v_permlane32_swap_b32 v44, v45
	v_add_f32_e32 v55, v44, v45
	v_fmamk_f32 v45, v55, 0xba800000, v15
	v_fmamk_f32 v44, v55, 0xba800000, v14
	v_fmamk_f32 v13, v55, 0xba800000, v13
	v_fmac_f32_e32 v12, 0xba800000, v55
	v_fmamk_f32 v11, v55, 0xba800000, v11
	v_fmamk_f32 v10, v55, 0xba800000, v10
	v_fmamk_f32 v9, v55, 0xba800000, v9
	v_fmac_f32_e32 v8, 0xba800000, v55
	v_pk_mul_f32 v[14:15], v[44:45], v[44:45]
	v_pk_mul_f32 v[56:57], v[12:13], v[12:13]
	v_pk_mul_f32 v[58:59], v[10:11], v[10:11]
	v_pk_mul_f32 v[60:61], v[8:9], v[8:9]
	v_fmamk_f32 v6, v55, 0xba800000, v6
	v_fmac_f32_e32 v4, 0xba800000, v55
	v_pk_mov_b32 v[66:67], v[56:57], v[14:15] op_sel:[1,0]
	v_mov_b32_e32 v57, v15
	v_pk_mov_b32 v[14:15], v[60:61], v[58:59] op_sel:[1,0]
	v_mov_b32_e32 v61, v59
	v_fmamk_f32 v7, v55, 0xba800000, v7
	v_fmamk_f32 v5, v55, 0xba800000, v5
	v_mul_f32_e32 v62, v4, v4
	v_mul_f32_e32 v64, v6, v6
	v_pk_add_f32 v[56:57], v[66:67], v[56:57]
	v_pk_add_f32 v[14:15], v[14:15], v[60:61]
	v_fmamk_f32 v3, v55, 0xba800000, v3
	v_fmamk_f32 v2, v55, 0xba800000, v2
	v_fmamk_f32 v1, v55, 0xba800000, v1
	v_fmac_f32_e32 v0, 0xba800000, v55
	v_pk_fma_f32 v[58:59], v[4:5], v[4:5], v[62:63] op_sel_hi:[1,1,0]
	v_pk_fma_f32 v[62:63], v[6:7], v[6:7], v[64:65] op_sel_hi:[1,1,0]
	v_pk_add_f32 v[56:57], v[56:57], v[56:57] op_sel_hi:[0,1]
	v_pk_add_f32 v[14:15], v[14:15], v[14:15] op_sel_hi:[0,1]
	v_mul_f32_e32 v58, v0, v0
	v_mul_f32_e32 v62, v1, v1
	v_mul_f32_e32 v56, v2, v2
	v_mul_f32_e32 v14, v3, v3
	v_pk_add_f32 v[58:59], v[58:59], v[62:63]
	v_pk_add_f32 v[14:15], v[56:57], v[14:15]
	s_nop 0
	v_pk_add_f32 v[14:15], v[58:59], v[14:15]
	s_nop 0
	v_add_f32_e32 v14, v14, v15
	s_nop 1
	v_add_f32_dpp v14, v14, v14 quad_perm:[1,0,3,2] row_mask:0xf bank_mask:0xf
	s_nop 1
	v_add_f32_dpp v14, v14, v14 quad_perm:[2,3,0,1] row_mask:0xf bank_mask:0xf
	s_nop 1
	v_add_f32_dpp v14, v14, v14 row_half_mirror row_mask:0xf bank_mask:0xf
	s_nop 1
	v_add_f32_dpp v14, v14, v14 row_mirror row_mask:0xf bank_mask:0xf
	v_mov_b32_e32 v15, v14
	s_nop 1
	v_permlane16_swap_b32 v14, v15
	v_add_f32_e32 v14, v14, v15
	v_mov_b32_e32 v15, v14
	s_nop 1
	v_permlane32_swap_b32 v14, v15
	v_add_f32_e32 v14, v14, v15
	v_fmamk_f32 v14, v14, 0x3a800000, v52
	v_mul_f32_e32 v15, 0x4b800000, v14
	v_cmp_gt_f32_e32 vcc, s28, v14
	s_nop 1
	v_cndmask_b32_e32 v14, v14, v15, vcc
	v_rsq_f32_e32 v14, v14
	s_nop 0
	v_mul_f32_e32 v15, 0x45800000, v14
	v_cndmask_b32_e32 v14, v14, v15, vcc
	s_and_saveexec_b64 s[4:5], s[10:11]
	s_cbranch_execz .LBB0_2074
	v_readlane_b32 s36, v254, 28
	v_readlane_b32 s42, v254, 34
	v_readlane_b32 s43, v254, 35
	v_mul_f32_e32 v56, 0x3a800000, v55
	v_mov_b32_e32 v57, v14
	v_lshl_add_u64 v[58:59], s[42:43], 0, v[32:33]
	v_add_co_u32_e32 v58, vcc, 0x1fe00000, v58
	v_readlane_b32 s37, v254, 29
	s_nop 0
	v_addc_co_u32_e32 v59, vcc, 0, v59, vcc
	v_readlane_b32 s38, v254, 30
	v_readlane_b32 s39, v254, 31
	v_readlane_b32 s40, v254, 32
	v_readlane_b32 s41, v254, 33
	global_store_dwordx2 v[58:59], v[56:57], off
	s_branch .LBB0_2074

.LBB0_2882:
	v_mul_hi_i32 v0, v53, s6
	v_lshrrev_b32_e32 v1, 31, v0
	v_ashrrev_i32_e32 v0, 11, v0
	v_add_u32_e32 v54, v0, v1
	v_mad_i32_i24 v1, v54, s7, v53
	v_cmp_gt_i32_e64 s[12:13], s2, v1
	v_cmp_lt_i32_e32 vcc, s8, v1
	s_and_saveexec_b64 s[4:5], vcc
	s_xor_b64 s[4:5], exec, s[4:5]
	v_mul_i32_i24_e32 v0, 0xffffdf00, v54
	v_lshl_add_u32 v0, v54, 13, v0
	v_add3_u32 v0, v53, v0, s9
	s_or_saveexec_b64 s[4:5], s[4:5]
	v_mov_b64_e32 v[2:3], s[88:89]
	s_xor_b64 exec, exec, s[4:5]
	v_lshl_add_u32 v0, v54, 8, v1
	v_mov_b64_e32 v[2:3], s[70:71]
	s_or_b64 exec, exec, s[4:5]
	v_ashrrev_i32_e32 v1, 31, v0
	v_lshlrev_b64 v[0:1], 12, v[0:1]
	v_lshl_add_u64 v[0:1], v[2:3], 0, v[0:1]
	v_lshl_add_u64 v[0:1], v[0:1], 0, v[36:37]
	global_load_dwordx4 v[12:15], v[0:1], off
	global_load_dwordx4 v[8:11], v[0:1], off offset:1024
	global_load_dwordx4 v[4:7], v[0:1], off offset:2048
	s_nop 0
	global_load_dwordx4 v[0:3], v[0:1], off offset:3072
	s_waitcnt vmcnt(3)
	v_mov_b32_e32 v44, v13
	v_mov_b32_e32 v45, v14
	v_mov_b32_e32 v56, v12
	v_mov_b32_e32 v57, v15
	s_waitcnt vmcnt(2)
	v_mov_b32_e32 v58, v9
	v_mov_b32_e32 v59, v10
	v_mov_b32_e32 v60, v8
	v_mov_b32_e32 v61, v11
	v_pk_add_f32 v[44:45], v[44:45], v[56:57]
	v_pk_add_f32 v[56:57], v[58:59], v[60:61]
	v_add_f32_e32 v55, v44, v45
	v_pk_add_f32 v[44:45], v[56:57], v[56:57] op_sel:[0,1] op_sel_hi:[1,0]
	s_waitcnt vmcnt(1)
	v_add_f32_e32 v62, v4, v5
	v_add_f32_e32 v64, v6, v7
	s_waitcnt vmcnt(0)
	v_mov_b32_e32 v67, v0
	v_mov_b32_e32 v63, v2
	v_mov_b32_e32 v65, v3
	v_add_f32_e32 v66, 0, v55
	v_mov_b32_e32 v45, v1
	v_pk_add_f32 v[58:59], v[62:63], v[64:65]
	v_pk_add_f32 v[44:45], v[66:67], v[44:45]
	s_nop 0
	v_pk_add_f32 v[44:45], v[44:45], v[58:59]
	s_nop 0
	v_add_f32_e32 v44, v44, v45
	s_nop 1
	v_add_f32_dpp v44, v44, v44 quad_perm:[1,0,3,2] row_mask:0xf bank_mask:0xf
	s_nop 1
	v_add_f32_dpp v44, v44, v44 quad_perm:[2,3,0,1] row_mask:0xf bank_mask:0xf
	s_nop 1
	v_add_f32_dpp v44, v44, v44 row_half_mirror row_mask:0xf bank_mask:0xf
	s_nop 1
	v_add_f32_dpp v44, v44, v44 row_mirror row_mask:0xf bank_mask:0xf
	v_mov_b32_e32 v45, v44
	s_nop 1
	v_permlane16_swap_b32 v44, v45
	v_add_f32_e32 v44, v44, v45
	v_mov_b32_e32 v45, v44
	s_nop 1
	v_permlane32_swap_b32 v44, v45
	v_add_f32_e32 v55, v44, v45
	v_fmamk_f32 v45, v55, 0xba800000, v15
	v_fmamk_f32 v44, v55, 0xba800000, v14
	v_fmamk_f32 v13, v55, 0xba800000, v13
	v_fmac_f32_e32 v12, 0xba800000, v55
	v_fmamk_f32 v11, v55, 0xba800000, v11
	v_fmamk_f32 v10, v55, 0xba800000, v10
	v_fmamk_f32 v9, v55, 0xba800000, v9
	v_fmac_f32_e32 v8, 0xba800000, v55
	v_pk_mul_f32 v[14:15], v[44:45], v[44:45]
	v_pk_mul_f32 v[56:57], v[12:13], v[12:13]
	v_pk_mul_f32 v[58:59], v[10:11], v[10:11]
	v_pk_mul_f32 v[60:61], v[8:9], v[8:9]
	v_fmamk_f32 v6, v55, 0xba800000, v6
	v_fmac_f32_e32 v4, 0xba800000, v55
	v_pk_mov_b32 v[66:67], v[56:57], v[14:15] op_sel:[1,0]
	v_mov_b32_e32 v57, v15
	v_pk_mov_b32 v[14:15], v[60:61], v[58:59] op_sel:[1,0]
	v_mov_b32_e32 v61, v59
	v_fmamk_f32 v7, v55, 0xba800000, v7
	v_fmamk_f32 v5, v55, 0xba800000, v5
	v_mul_f32_e32 v62, v4, v4
	v_mul_f32_e32 v64, v6, v6
	v_pk_add_f32 v[56:57], v[66:67], v[56:57]
	v_pk_add_f32 v[14:15], v[14:15], v[60:61]
	v_fmamk_f32 v3, v55, 0xba800000, v3
	v_fmamk_f32 v2, v55, 0xba800000, v2
	v_fmamk_f32 v1, v55, 0xba800000, v1
	v_fmac_f32_e32 v0, 0xba800000, v55
	v_pk_fma_f32 v[58:59], v[4:5], v[4:5], v[62:63] op_sel_hi:[1,1,0]
	v_pk_fma_f32 v[62:63], v[6:7], v[6:7], v[64:65] op_sel_hi:[1,1,0]
	v_pk_add_f32 v[56:57], v[56:57], v[56:57] op_sel_hi:[0,1]
	v_pk_add_f32 v[14:15], v[14:15], v[14:15] op_sel_hi:[0,1]
	v_mul_f32_e32 v58, v0, v0
	v_mul_f32_e32 v62, v1, v1
	v_mul_f32_e32 v56, v2, v2
	v_mul_f32_e32 v14, v3, v3
	v_pk_add_f32 v[58:59], v[58:59], v[62:63]
	v_pk_add_f32 v[14:15], v[56:57], v[14:15]
	s_nop 0
	v_pk_add_f32 v[14:15], v[58:59], v[14:15]
	s_nop 0
	v_add_f32_e32 v14, v14, v15
	s_nop 1
	v_add_f32_dpp v14, v14, v14 quad_perm:[1,0,3,2] row_mask:0xf bank_mask:0xf
	s_nop 1
	v_add_f32_dpp v14, v14, v14 quad_perm:[2,3,0,1] row_mask:0xf bank_mask:0xf
	s_nop 1
	v_add_f32_dpp v14, v14, v14 row_half_mirror row_mask:0xf bank_mask:0xf
	s_nop 1
	v_add_f32_dpp v14, v14, v14 row_mirror row_mask:0xf bank_mask:0xf
	v_mov_b32_e32 v15, v14
	s_nop 1
	v_permlane16_swap_b32 v14, v15
	v_add_f32_e32 v14, v14, v15
	v_mov_b32_e32 v15, v14
	s_nop 1
	v_permlane32_swap_b32 v14, v15
	v_add_f32_e32 v14, v14, v15
	v_fmamk_f32 v14, v14, 0x3a800000, v52
	v_mul_f32_e32 v15, 0x4b800000, v14
	v_cmp_gt_f32_e32 vcc, s24, v14
	s_nop 1
	v_cndmask_b32_e32 v14, v14, v15, vcc
	v_rsq_f32_e32 v14, v14
	s_nop 0
	v_mul_f32_e32 v15, 0x45800000, v14
	v_cndmask_b32_e32 v14, v14, v15, vcc
	s_and_saveexec_b64 s[4:5], s[10:11]
	s_cbranch_execz .LBB0_2881
	v_lshl_add_u64 v[58:59], s[90:91], 0, v[32:33]
	v_add_co_u32_e32 v58, vcc, 0x1fe00000, v58
	v_mul_f32_e32 v56, 0x3a800000, v55
	s_nop 0
	v_addc_co_u32_e32 v59, vcc, 0, v59, vcc
	v_mov_b32_e32 v57, v14
	global_store_dwordx2 v[58:59], v[56:57], off
	s_branch .LBB0_2881

.LBB0_3110:
	v_mul_hi_i32 v0, v53, s6
	v_lshrrev_b32_e32 v1, 31, v0
	v_ashrrev_i32_e32 v0, 11, v0
	v_add_u32_e32 v54, v0, v1
	v_mad_i32_i24 v1, v54, s7, v53
	v_cmp_gt_i32_e64 s[10:11], s2, v1
	v_cmp_lt_i32_e32 vcc, s20, v1
	s_and_saveexec_b64 s[4:5], vcc
	s_xor_b64 s[4:5], exec, s[4:5]
	v_mul_i32_i24_e32 v0, 0xffffdf00, v54
	v_lshl_add_u32 v0, v54, 13, v0
	v_add3_u32 v0, v53, v0, s21
	s_or_saveexec_b64 s[4:5], s[4:5]
	v_mov_b64_e32 v[2:3], s[88:89]
	s_xor_b64 exec, exec, s[4:5]
	v_lshl_add_u32 v0, v54, 8, v1
	v_mov_b64_e32 v[2:3], s[70:71]
	s_or_b64 exec, exec, s[4:5]
	v_ashrrev_i32_e32 v1, 31, v0
	v_lshlrev_b64 v[0:1], 12, v[0:1]
	v_lshl_add_u64 v[0:1], v[2:3], 0, v[0:1]
	v_lshl_add_u64 v[0:1], v[0:1], 0, v[36:37]
	global_load_dwordx4 v[12:15], v[0:1], off
	global_load_dwordx4 v[8:11], v[0:1], off offset:1024
	global_load_dwordx4 v[4:7], v[0:1], off offset:2048
	s_nop 0
	global_load_dwordx4 v[0:3], v[0:1], off offset:3072
	s_waitcnt vmcnt(3)
	v_mov_b32_e32 v44, v13
	v_mov_b32_e32 v45, v14
	v_mov_b32_e32 v56, v12
	v_mov_b32_e32 v57, v15
	s_waitcnt vmcnt(2)
	v_mov_b32_e32 v58, v9
	v_mov_b32_e32 v59, v10
	v_mov_b32_e32 v60, v8
	v_mov_b32_e32 v61, v11
	v_pk_add_f32 v[44:45], v[44:45], v[56:57]
	v_pk_add_f32 v[56:57], v[58:59], v[60:61]
	v_add_f32_e32 v55, v44, v45
	v_pk_add_f32 v[44:45], v[56:57], v[56:57] op_sel:[0,1] op_sel_hi:[1,0]
	s_waitcnt vmcnt(1)
	v_add_f32_e32 v62, v4, v5
	v_add_f32_e32 v64, v6, v7
	s_waitcnt vmcnt(0)
	v_mov_b32_e32 v67, v0
	v_mov_b32_e32 v63, v2
	v_mov_b32_e32 v65, v3
	v_add_f32_e32 v66, 0, v55
	v_mov_b32_e32 v45, v1
	v_pk_add_f32 v[58:59], v[62:63], v[64:65]
	v_pk_add_f32 v[44:45], v[66:67], v[44:45]
	s_nop 0
	v_pk_add_f32 v[44:45], v[44:45], v[58:59]
	s_nop 0
	v_add_f32_e32 v44, v44, v45
	s_nop 1
	v_add_f32_dpp v44, v44, v44 quad_perm:[1,0,3,2] row_mask:0xf bank_mask:0xf
	s_nop 1
	v_add_f32_dpp v44, v44, v44 quad_perm:[2,3,0,1] row_mask:0xf bank_mask:0xf
	s_nop 1
	v_add_f32_dpp v44, v44, v44 row_half_mirror row_mask:0xf bank_mask:0xf
	s_nop 1
	v_add_f32_dpp v44, v44, v44 row_mirror row_mask:0xf bank_mask:0xf
	v_mov_b32_e32 v45, v44
	s_nop 1
	v_permlane16_swap_b32 v44, v45
	v_add_f32_e32 v44, v44, v45
	v_mov_b32_e32 v45, v44
	s_nop 1
	v_permlane32_swap_b32 v44, v45
	v_add_f32_e32 v55, v44, v45
	v_fmamk_f32 v45, v55, 0xba800000, v15
	v_fmamk_f32 v44, v55, 0xba800000, v14
	v_fmamk_f32 v13, v55, 0xba800000, v13
	v_fmac_f32_e32 v12, 0xba800000, v55
	v_fmamk_f32 v11, v55, 0xba800000, v11
	v_fmamk_f32 v10, v55, 0xba800000, v10
	v_fmamk_f32 v9, v55, 0xba800000, v9
	v_fmac_f32_e32 v8, 0xba800000, v55
	v_pk_mul_f32 v[14:15], v[44:45], v[44:45]
	v_pk_mul_f32 v[56:57], v[12:13], v[12:13]
	v_pk_mul_f32 v[58:59], v[10:11], v[10:11]
	v_pk_mul_f32 v[60:61], v[8:9], v[8:9]
	v_fmamk_f32 v6, v55, 0xba800000, v6
	v_fmac_f32_e32 v4, 0xba800000, v55
	v_pk_mov_b32 v[66:67], v[56:57], v[14:15] op_sel:[1,0]
	v_mov_b32_e32 v57, v15
	v_pk_mov_b32 v[14:15], v[60:61], v[58:59] op_sel:[1,0]
	v_mov_b32_e32 v61, v59
	v_fmamk_f32 v7, v55, 0xba800000, v7
	v_fmamk_f32 v5, v55, 0xba800000, v5
	v_mul_f32_e32 v62, v4, v4
	v_mul_f32_e32 v64, v6, v6
	v_pk_add_f32 v[56:57], v[66:67], v[56:57]
	v_pk_add_f32 v[14:15], v[14:15], v[60:61]
	v_fmamk_f32 v3, v55, 0xba800000, v3
	v_fmamk_f32 v2, v55, 0xba800000, v2
	v_fmamk_f32 v1, v55, 0xba800000, v1
	v_fmac_f32_e32 v0, 0xba800000, v55
	v_pk_fma_f32 v[58:59], v[4:5], v[4:5], v[62:63] op_sel_hi:[1,1,0]
	v_pk_fma_f32 v[62:63], v[6:7], v[6:7], v[64:65] op_sel_hi:[1,1,0]
	v_pk_add_f32 v[56:57], v[56:57], v[56:57] op_sel_hi:[0,1]
	v_pk_add_f32 v[14:15], v[14:15], v[14:15] op_sel_hi:[0,1]
	v_mul_f32_e32 v58, v0, v0
	v_mul_f32_e32 v62, v1, v1
	v_mul_f32_e32 v56, v2, v2
	v_mul_f32_e32 v14, v3, v3
	v_pk_add_f32 v[58:59], v[58:59], v[62:63]
	v_pk_add_f32 v[14:15], v[56:57], v[14:15]
	s_nop 0
	v_pk_add_f32 v[14:15], v[58:59], v[14:15]
	s_nop 0
	v_add_f32_e32 v14, v14, v15
	s_nop 1
	v_add_f32_dpp v14, v14, v14 quad_perm:[1,0,3,2] row_mask:0xf bank_mask:0xf
	s_nop 1
	v_add_f32_dpp v14, v14, v14 quad_perm:[2,3,0,1] row_mask:0xf bank_mask:0xf
	s_nop 1
	v_add_f32_dpp v14, v14, v14 row_half_mirror row_mask:0xf bank_mask:0xf
	s_nop 1
	v_add_f32_dpp v14, v14, v14 row_mirror row_mask:0xf bank_mask:0xf
	v_mov_b32_e32 v15, v14
	s_nop 1
	v_permlane16_swap_b32 v14, v15
	v_add_f32_e32 v14, v14, v15
	v_mov_b32_e32 v15, v14
	s_nop 1
	v_permlane32_swap_b32 v14, v15
	v_add_f32_e32 v14, v14, v15
	v_fmamk_f32 v14, v14, 0x3a800000, v52
	v_mul_f32_e32 v15, 0x4b800000, v14
	v_cmp_gt_f32_e32 vcc, s22, v14
	s_nop 1
	v_cndmask_b32_e32 v14, v14, v15, vcc
	v_rsq_f32_e32 v14, v14
	s_nop 0
	v_mul_f32_e32 v15, 0x45800000, v14
	v_cndmask_b32_e32 v14, v14, v15, vcc
	s_and_saveexec_b64 s[4:5], s[8:9]
	s_cbranch_execz .LBB0_3109
	v_lshl_add_u64 v[58:59], s[90:91], 0, v[32:33]
	v_add_co_u32_e32 v58, vcc, 0x1fe00000, v58
	v_mul_f32_e32 v56, 0x3a800000, v55
	s_nop 0
	v_addc_co_u32_e32 v59, vcc, 0, v59, vcc
	v_mov_b32_e32 v57, v14
	global_store_dwordx2 v[58:59], v[56:57], off
	s_branch .LBB0_3109

.LBB0_3596:
	v_mul_hi_i32 v0, v53, s20
	v_lshrrev_b32_e32 v1, 31, v0
	v_ashrrev_i32_e32 v0, 11, v0
	v_add_u32_e32 v54, v0, v1
	v_mad_i32_i24 v1, v54, s21, v53
	v_cmp_gt_i32_e64 s[8:9], s2, v1
	v_cmp_lt_i32_e32 vcc, s22, v1
	s_and_saveexec_b64 s[4:5], vcc
	s_xor_b64 s[4:5], exec, s[4:5]
	v_mul_i32_i24_e32 v0, 0xffffdf00, v54
	v_lshl_add_u32 v0, v54, 13, v0
	v_add3_u32 v0, v53, v0, s23
	s_or_saveexec_b64 s[4:5], s[4:5]
	v_mov_b64_e32 v[2:3], s[88:89]
	s_xor_b64 exec, exec, s[4:5]
	v_lshl_add_u32 v0, v54, 8, v1
	v_mov_b64_e32 v[2:3], s[70:71]
	s_or_b64 exec, exec, s[4:5]
	v_ashrrev_i32_e32 v1, 31, v0
	v_lshlrev_b64 v[0:1], 12, v[0:1]
	v_lshl_add_u64 v[0:1], v[2:3], 0, v[0:1]
	v_lshl_add_u64 v[0:1], v[0:1], 0, v[36:37]
	global_load_dwordx4 v[12:15], v[0:1], off
	global_load_dwordx4 v[8:11], v[0:1], off offset:1024
	global_load_dwordx4 v[4:7], v[0:1], off offset:2048
	s_nop 0
	global_load_dwordx4 v[0:3], v[0:1], off offset:3072
	s_waitcnt vmcnt(3)
	v_mov_b32_e32 v44, v13
	v_mov_b32_e32 v45, v14
	v_mov_b32_e32 v56, v12
	v_mov_b32_e32 v57, v15
	s_waitcnt vmcnt(2)
	v_mov_b32_e32 v58, v9
	v_mov_b32_e32 v59, v10
	v_mov_b32_e32 v60, v8
	v_mov_b32_e32 v61, v11
	v_pk_add_f32 v[44:45], v[44:45], v[56:57]
	v_pk_add_f32 v[56:57], v[58:59], v[60:61]
	v_add_f32_e32 v55, v44, v45
	v_pk_add_f32 v[44:45], v[56:57], v[56:57] op_sel:[0,1] op_sel_hi:[1,0]
	s_waitcnt vmcnt(1)
	v_add_f32_e32 v62, v4, v5
	v_add_f32_e32 v64, v6, v7
	s_waitcnt vmcnt(0)
	v_mov_b32_e32 v67, v0
	v_mov_b32_e32 v63, v2
	v_mov_b32_e32 v65, v3
	v_add_f32_e32 v66, 0, v55
	v_mov_b32_e32 v45, v1
	v_pk_add_f32 v[58:59], v[62:63], v[64:65]
	v_pk_add_f32 v[44:45], v[66:67], v[44:45]
	s_nop 0
	v_pk_add_f32 v[44:45], v[44:45], v[58:59]
	s_nop 0
	v_add_f32_e32 v44, v44, v45
	s_nop 1
	v_add_f32_dpp v44, v44, v44 quad_perm:[1,0,3,2] row_mask:0xf bank_mask:0xf
	s_nop 1
	v_add_f32_dpp v44, v44, v44 quad_perm:[2,3,0,1] row_mask:0xf bank_mask:0xf
	s_nop 1
	v_add_f32_dpp v44, v44, v44 row_half_mirror row_mask:0xf bank_mask:0xf
	s_nop 1
	v_add_f32_dpp v44, v44, v44 row_mirror row_mask:0xf bank_mask:0xf
	v_mov_b32_e32 v45, v44
	s_nop 1
	v_permlane16_swap_b32 v44, v45
	v_add_f32_e32 v44, v44, v45
	v_mov_b32_e32 v45, v44
	s_nop 1
	v_permlane32_swap_b32 v44, v45
	v_add_f32_e32 v55, v44, v45
	v_fmamk_f32 v45, v55, 0xba800000, v15
	v_fmamk_f32 v44, v55, 0xba800000, v14
	v_fmamk_f32 v13, v55, 0xba800000, v13
	v_fmac_f32_e32 v12, 0xba800000, v55
	v_fmamk_f32 v11, v55, 0xba800000, v11
	v_fmamk_f32 v10, v55, 0xba800000, v10
	v_fmamk_f32 v9, v55, 0xba800000, v9
	v_fmac_f32_e32 v8, 0xba800000, v55
	v_pk_mul_f32 v[14:15], v[44:45], v[44:45]
	v_pk_mul_f32 v[56:57], v[12:13], v[12:13]
	v_pk_mul_f32 v[58:59], v[10:11], v[10:11]
	v_pk_mul_f32 v[60:61], v[8:9], v[8:9]
	v_fmamk_f32 v6, v55, 0xba800000, v6
	v_fmac_f32_e32 v4, 0xba800000, v55
	v_pk_mov_b32 v[66:67], v[56:57], v[14:15] op_sel:[1,0]
	v_mov_b32_e32 v57, v15
	v_pk_mov_b32 v[14:15], v[60:61], v[58:59] op_sel:[1,0]
	v_mov_b32_e32 v61, v59
	v_fmamk_f32 v7, v55, 0xba800000, v7
	v_fmamk_f32 v5, v55, 0xba800000, v5
	v_mul_f32_e32 v62, v4, v4
	v_mul_f32_e32 v64, v6, v6
	v_pk_add_f32 v[56:57], v[66:67], v[56:57]
	v_pk_add_f32 v[14:15], v[14:15], v[60:61]
	v_fmamk_f32 v3, v55, 0xba800000, v3
	v_fmamk_f32 v2, v55, 0xba800000, v2
	v_fmamk_f32 v1, v55, 0xba800000, v1
	v_fmac_f32_e32 v0, 0xba800000, v55
	v_pk_fma_f32 v[58:59], v[4:5], v[4:5], v[62:63] op_sel_hi:[1,1,0]
	v_pk_fma_f32 v[62:63], v[6:7], v[6:7], v[64:65] op_sel_hi:[1,1,0]
	v_pk_add_f32 v[56:57], v[56:57], v[56:57] op_sel_hi:[0,1]
	v_pk_add_f32 v[14:15], v[14:15], v[14:15] op_sel_hi:[0,1]
	v_mul_f32_e32 v58, v0, v0
	v_mul_f32_e32 v62, v1, v1
	v_mul_f32_e32 v56, v2, v2
	v_mul_f32_e32 v14, v3, v3
	v_pk_add_f32 v[58:59], v[58:59], v[62:63]
	v_pk_add_f32 v[14:15], v[56:57], v[14:15]
	s_nop 0
	v_pk_add_f32 v[14:15], v[58:59], v[14:15]
	s_nop 0
	v_add_f32_e32 v14, v14, v15
	s_nop 1
	v_add_f32_dpp v14, v14, v14 quad_perm:[1,0,3,2] row_mask:0xf bank_mask:0xf
	s_nop 1
	v_add_f32_dpp v14, v14, v14 quad_perm:[2,3,0,1] row_mask:0xf bank_mask:0xf
	s_nop 1
	v_add_f32_dpp v14, v14, v14 row_half_mirror row_mask:0xf bank_mask:0xf
	s_nop 1
	v_add_f32_dpp v14, v14, v14 row_mirror row_mask:0xf bank_mask:0xf
	v_mov_b32_e32 v15, v14
	s_nop 1
	v_permlane16_swap_b32 v14, v15
	v_add_f32_e32 v14, v14, v15
	v_mov_b32_e32 v15, v14
	s_nop 1
	v_permlane32_swap_b32 v14, v15
	v_add_f32_e32 v14, v14, v15
	v_fmamk_f32 v14, v14, 0x3a800000, v52
	v_mul_f32_e32 v15, 0x4b800000, v14
	v_cmp_gt_f32_e32 vcc, s24, v14
	s_nop 1
	v_cndmask_b32_e32 v14, v14, v15, vcc
	v_rsq_f32_e32 v14, v14
	s_nop 0
	v_mul_f32_e32 v15, 0x45800000, v14
	v_cndmask_b32_e32 v14, v14, v15, vcc
	s_and_saveexec_b64 s[4:5], s[6:7]
	s_cbranch_execz .LBB0_3595
	v_lshl_add_u64 v[58:59], s[90:91], 0, v[32:33]
	v_add_co_u32_e32 v58, vcc, 0x1fe00000, v58
	v_mul_f32_e32 v56, 0x3a800000, v55
	s_nop 0
	v_addc_co_u32_e32 v59, vcc, 0, v59, vcc
	v_mov_b32_e32 v57, v14
	global_store_dwordx2 v[58:59], v[56:57], off
	s_branch .LBB0_3595

.LBB0_3804:
	s_or_b64 exec, exec, s[4:5]
	v_ashrrev_i32_e32 v1, 31, v0
	v_lshlrev_b64 v[0:1], 12, v[0:1]
	v_lshl_add_u64 v[0:1], v[2:3], 0, v[0:1]
	v_lshl_add_u64 v[20:21], v[0:1], 0, v[152:153]
	global_load_dwordx4 v[30:33], v[20:21], off
	global_load_dwordx4 v[34:37], v[20:21], off offset:1024
	global_load_dwordx4 v[38:41], v[20:21], off offset:2048
	global_load_dwordx4 v[0:3], v[20:21], off offset:3072
	v_add_u32_e32 v150, s52, v150
	s_waitcnt vmcnt(3)
	v_mov_b32_e32 v42, v31
	v_mov_b32_e32 v43, v32
	v_mov_b32_e32 v44, v30
	v_mov_b32_e32 v45, v33
	s_waitcnt vmcnt(2)
	v_mov_b32_e32 v46, v35
	v_mov_b32_e32 v47, v36
	v_mov_b32_e32 v48, v34
	v_mov_b32_e32 v49, v37
	v_pk_add_f32 v[42:43], v[42:43], v[44:45]
	v_pk_add_f32 v[44:45], v[46:47], v[48:49]
	v_add_f32_e32 v29, v42, v43
	v_pk_add_f32 v[42:43], v[44:45], v[44:45] op_sel:[0,1] op_sel_hi:[1,0]
	s_waitcnt vmcnt(1)
	v_add_f32_e32 v50, v38, v39
	v_add_f32_e32 v52, v40, v41
	s_waitcnt vmcnt(0)
	v_mov_b32_e32 v55, v0
	v_mov_b32_e32 v51, v2
	v_mov_b32_e32 v53, v3
	v_add_f32_e32 v54, 0, v29
	v_mov_b32_e32 v43, v1
	v_pk_add_f32 v[46:47], v[50:51], v[52:53]
	v_pk_add_f32 v[42:43], v[54:55], v[42:43]
	s_nop 0
	v_pk_add_f32 v[42:43], v[42:43], v[46:47]
	s_nop 0
	v_add_f32_e32 v29, v42, v43
	s_nop 1
	v_add_f32_dpp v29, v29, v29 quad_perm:[1,0,3,2] row_mask:0xf bank_mask:0xf
	s_nop 1
	v_add_f32_dpp v29, v29, v29 quad_perm:[2,3,0,1] row_mask:0xf bank_mask:0xf
	s_nop 1
	v_add_f32_dpp v29, v29, v29 row_half_mirror row_mask:0xf bank_mask:0xf
	s_nop 1
	v_add_f32_dpp v29, v29, v29 row_mirror row_mask:0xf bank_mask:0xf
	v_mov_b32_e32 v42, v29
	s_nop 1
	v_permlane16_swap_b32 v29, v42
	v_add_f32_e32 v29, v29, v42
	global_load_dwordx4 v[42:45], v[4:5], off
	global_load_dwordx4 v[46:49], v[6:7], off
	ds_bpermute_b32 v50, v27, v29
	s_waitcnt lgkmcnt(0)
	v_add_f32_e32 v29, v29, v50
	v_fmamk_f32 v31, v29, 0xba800000, v31
	v_fmamk_f32 v30, v29, 0xba800000, v30
	v_fmamk_f32 v33, v29, 0xba800000, v33
	v_fmac_f32_e32 v32, 0xba800000, v29
	v_fmamk_f32 v35, v29, 0xba800000, v35
	v_fmamk_f32 v34, v29, 0xba800000, v34
	v_fmamk_f32 v37, v29, 0xba800000, v37
	v_fmac_f32_e32 v36, 0xba800000, v29
	v_pk_mul_f32 v[50:51], v[32:33], v[32:33]
	v_pk_mul_f32 v[52:53], v[30:31], v[30:31]
	v_pk_mul_f32 v[54:55], v[36:37], v[36:37]
	v_pk_mul_f32 v[56:57], v[34:35], v[34:35]
	v_fmamk_f32 v38, v29, 0xba800000, v38
	v_fmac_f32_e32 v40, 0xba800000, v29
	v_pk_mov_b32 v[62:63], v[52:53], v[50:51] op_sel:[1,0]
	v_mov_b32_e32 v53, v51
	v_pk_mov_b32 v[50:51], v[56:57], v[54:55] op_sel:[1,0]
	v_mov_b32_e32 v57, v55
	v_fmamk_f32 v39, v29, 0xba800000, v39
	v_fmamk_f32 v41, v29, 0xba800000, v41
	v_mul_f32_e32 v58, v38, v38
	v_mul_f32_e32 v60, v40, v40
	v_pk_add_f32 v[52:53], v[62:63], v[52:53]
	v_pk_add_f32 v[50:51], v[50:51], v[56:57]
	v_fmamk_f32 v3, v29, 0xba800000, v3
	v_fmamk_f32 v2, v29, 0xba800000, v2
	v_fmamk_f32 v1, v29, 0xba800000, v1
	v_fmac_f32_e32 v0, 0xba800000, v29
	v_pk_fma_f32 v[54:55], v[38:39], v[38:39], v[58:59] op_sel_hi:[1,1,0]
	v_pk_fma_f32 v[58:59], v[40:41], v[40:41], v[60:61] op_sel_hi:[1,1,0]
	v_pk_add_f32 v[52:53], v[52:53], v[52:53] op_sel_hi:[0,1]
	v_pk_add_f32 v[50:51], v[50:51], v[50:51] op_sel_hi:[0,1]
	v_mul_f32_e32 v54, v0, v0
	v_mul_f32_e32 v58, v1, v1
	v_mul_f32_e32 v52, v2, v2
	v_mul_f32_e32 v50, v3, v3
	v_pk_add_f32 v[54:55], v[54:55], v[58:59]
	v_pk_add_f32 v[50:51], v[52:53], v[50:51]
	s_nop 0
	v_pk_add_f32 v[50:51], v[54:55], v[50:51]
	s_nop 0
	v_add_f32_e32 v29, v50, v51
	s_nop 1
	v_add_f32_dpp v29, v29, v29 quad_perm:[1,0,3,2] row_mask:0xf bank_mask:0xf
	s_nop 1
	v_add_f32_dpp v29, v29, v29 quad_perm:[2,3,0,1] row_mask:0xf bank_mask:0xf
	s_nop 1
	v_add_f32_dpp v29, v29, v29 row_half_mirror row_mask:0xf bank_mask:0xf
	s_nop 1
	v_add_f32_dpp v29, v29, v29 row_mirror row_mask:0xf bank_mask:0xf
	v_mov_b32_e32 v50, v29
	s_nop 1
	v_permlane16_swap_b32 v29, v50
	v_add_f32_e32 v29, v29, v50
	v_mov_b32_e32 v50, v29
	s_nop 1
	v_permlane32_swap_b32 v29, v50
	v_add_f32_e32 v29, v29, v50
	v_fmamk_f32 v29, v29, 0x3a800000, v28
	v_mul_f32_e32 v50, 0x4b800000, v29
	v_cmp_gt_f32_e32 vcc, s10, v29
	s_nop 1
	v_cndmask_b32_e32 v29, v29, v50, vcc
	v_rsq_f32_e32 v29, v29
	s_nop 0
	v_mul_f32_e32 v50, 0x45800000, v29
	v_cndmask_b32_e32 v50, v29, v50, vcc
	v_pk_mul_f32 v[30:31], v[30:31], v[50:51] op_sel_hi:[1,0]
	v_pk_mul_f32 v[32:33], v[32:33], v[50:51] op_sel_hi:[1,0]
	s_waitcnt vmcnt(0)
	v_pk_fma_f32 v[30:31], v[42:43], v[30:31], v[46:47]
	v_pk_fma_f32 v[32:33], v[44:45], v[32:33], v[48:49]
	global_store_dwordx4 v[20:21], v[30:33], off
	global_load_dwordx4 v[30:33], v[8:9], off
	s_nop 0
	global_load_dwordx4 v[42:45], v[10:11], off
	v_pk_mul_f32 v[36:37], v[36:37], v[50:51] op_sel_hi:[1,0]
	v_pk_mul_f32 v[34:35], v[34:35], v[50:51] op_sel_hi:[1,0]
	v_pk_mul_f32 v[40:41], v[40:41], v[50:51] op_sel_hi:[1,0]
	v_pk_mul_f32 v[38:39], v[38:39], v[50:51] op_sel_hi:[1,0]
	v_cmp_lt_i32_e32 vcc, s11, v150
	v_pk_mul_f32 v[2:3], v[2:3], v[50:51] op_sel_hi:[1,0]
	v_pk_mul_f32 v[0:1], v[0:1], v[50:51] op_sel_hi:[1,0]
	s_or_b64 s[2:3], vcc, s[2:3]
	s_waitcnt vmcnt(0)
	v_pk_fma_f32 v[30:31], v[30:31], v[34:35], v[42:43]
	v_pk_fma_f32 v[32:33], v[32:33], v[36:37], v[44:45]
	global_store_dwordx4 v[20:21], v[30:33], off offset:1024
	global_load_dwordx4 v[30:33], v[12:13], off
	s_nop 0
	global_load_dwordx4 v[34:37], v[14:15], off
	s_waitcnt vmcnt(0)
	v_pk_fma_f32 v[30:31], v[30:31], v[38:39], v[34:35]
	v_pk_fma_f32 v[32:33], v[32:33], v[40:41], v[36:37]
	global_store_dwordx4 v[20:21], v[30:33], off offset:2048
	global_load_dwordx4 v[30:33], v[16:17], off
	s_nop 0
	global_load_dwordx4 v[34:37], v[18:19], off
	s_waitcnt vmcnt(0)
	v_pk_fma_f32 v[0:1], v[30:31], v[0:1], v[34:35]
	v_pk_fma_f32 v[2:3], v[32:33], v[2:3], v[36:37]
	global_store_dwordx4 v[20:21], v[0:3], off offset:3072
	s_andn2_b64 exec, exec, s[2:3]
	s_cbranch_execz .LBB0_3809
